# GEMM tile end: waves 0-3 reload the epilogue descriptor before their resync barrier (inside the partner group's last MFMA segment)
# speedup vs baseline: 1.0033x; 1.0033x over previous
; #define LAS __attribute__((address_space(3)))
; #define PG8_BAR __builtin_amdgcn_s_barrier()
; DI Epi epi_load(LAS unsigned char* lds) {
;     const volatile LAS u32x4* p4 = (const volatile LAS u32x4*)(lds + CTL_EPI);
;     u32x4 q[7];
; #pragma unroll
;     for (int i = 0; i < 7; ++i) q[i] = p4[i];
;     unsigned w[28];
; #pragma unroll
;     for (int i = 0; i < 7; ++i) { w[4 * i] = __builtin_amdgcn_readfirstlane(q[i].x); w[4 * i + 1] = __builtin_amdgcn_readfirstlane(q[i].y); w[4 * i + 2] = __builtin_amdgcn_readfirstlane(q[i].z); w[4 * i + 3] = __builtin_amdgcn_readfirstlane(q[i].w); }
;     ...
;     Epi e;
;     e.mode = (int)w[0]; e.perm = w[1] != 0u; e.ldc = (int)w[2]; e.gate_chunk = (int)w[3]; e.gi = (int)w[4]; e.gs = __uint_as_float(w[5]);
;     e.O = (bf16_t*)W64(6); e.base_lat = (const float*)W64(8); e.base_ctx = (const float*)W64(10); e.out_lat = (float*)W64(12); e.out_ctx = (float*)W64(14);
;     e.modp = (const float*)W64(16); e.bias = (const float*)W64(18); e.BR = (bf16_t*)W64(20); e.MG = (bf16_t*)W64(22); e.row_off = (int)w[24];
; DI void gemm_phase(LAS unsigned char* lds, const Gemm g, const StaticOrder& S, const bool eperm) {
;     ...
;         if (wr == 0) PG8_BAR;
;         { const Epi E = epi_load(lds); E(acc, cur, wr, wc, fr, fq); }
.LBB0_794:
.LBB0_796:
	v_readlane_b32 s0, v252, 38
	s_lshl_b32 s1, s41, 8
	s_mov_b64 s[82:83], -1
	v_mov_b32_e32 v158, s0
	v_mov_b32_e32 v159, s75
	v_mov_b32_e32 v160, s90
	v_mov_b32_e32 v161, s91
	v_mov_b32_e32 v162, s48
	v_mov_b32_e32 v163, s49
	v_mov_b32_e32 v164, s64
	ds_read_b128 v[130:133], v158
	ds_read_b128 v[134:137], v159
	ds_read_b128 v[138:141], v160
	ds_read_b128 v[142:145], v161
	ds_read_b128 v[146:149], v162
	ds_read_b128 v[150:153], v163
	ds_read_b128 v[154:157], v164
	s_waitcnt lgkmcnt(0)
	v_readfirstlane_b32 s55, v130
	v_readfirstlane_b32 s50, v132
	v_readfirstlane_b32 s33, v133
	s_waitcnt lgkmcnt(0)
	v_readfirstlane_b32 s46, v134
	v_readfirstlane_b32 s0, v154
	s_add_i32 s41, s0, s1
	v_readfirstlane_b32 s40, v135
	v_readfirstlane_b32 s30, v136
	v_readfirstlane_b32 s31, v137
	v_readfirstlane_b32 vcc_lo, v138
	v_readfirstlane_b32 vcc_hi, v139
	v_readfirstlane_b32 s58, v140
	v_readfirstlane_b32 s56, v141
	v_readfirstlane_b32 s72, v142
	v_readfirstlane_b32 s3, v143
	v_readfirstlane_b32 s57, v144
	v_readfirstlane_b32 s74, v145
	v_readfirstlane_b32 s76, v146
	v_readfirstlane_b32 s77, v147
	v_readfirstlane_b32 s80, v148
	v_readfirstlane_b32 s81, v149
	v_readfirstlane_b32 s44, v150
	v_readfirstlane_b32 s45, v151
	v_readfirstlane_b32 s34, v152
	v_readfirstlane_b32 s35, v153
	v_add_u32_e32 v176, s41, v183
	s_and_b64 s[0:1], exec, s[22:23]
	s_cbranch_scc0 .Lg_nox
	s_barrier
.Lg_nox:
	s_mov_b64 s[0:1], 0
	s_cmp_lt_i32 s55, 1
	s_mov_b64 s[6:7], 0
	s_cbranch_scc1 .LBB0_801
	s_cmp_gt_i32 s55, 1
	s_cbranch_scc0 .LBB0_808
	s_cmp_eq_u32 s55, 2
	s_mov_b64 s[6:7], -1
	s_cbranch_scc0 .LBB0_800
	s_min_i32 s6, s41, 0x10000
	s_ashr_i32 s6, s6, 13
	s_add_u32 s58, s58, 0xf0000000
	s_addc_u32 s56, s56, -1
	s_add_u32 s57, s57, 0xf0000000
	s_addc_u32 s74, s74, -1
	v_mul_hi_i32_i24_e32 v131, s6, v235
	v_mul_i32_i24_e32 v130, s6, v235
	s_lshl_b32 s6, s33, 10
	s_ashr_i32 s7, s6, 31
	v_lshl_add_u64 v[130:131], s[76:77], 0, v[130:131]
	s_lshl_b64 s[6:7], s[6:7], 2
	v_lshl_or_b32 v150, s51, 8, v185
	v_lshl_add_u64 v[130:131], v[130:131], 0, s[6:7]
	v_ashrrev_i32_e32 v151, 31, v150
	v_lshl_add_u64 v[164:165], v[150:151], 2, v[130:131]
	global_load_dwordx4 v[130:133], v[164:165], off
	global_load_dwordx4 v[134:137], v[164:165], off offset:64
	global_load_dwordx4 v[138:141], v[164:165], off offset:128
	global_load_dwordx4 v[142:145], v[164:165], off offset:192
	v_ashrrev_i32_e32 v177, 31, v176
	s_cmp_lt_i32 s41, 0x10000
	s_cselect_b32 s7, s3, s74
	s_cselect_b32 s6, s72, s57
	s_cselect_b32 vcc_hi, vcc_hi, s56
	s_cselect_b32 vcc_lo, vcc_lo, s58
	v_lshlrev_b64 v[146:147], 10, v[176:177]
	v_lshl_add_u64 v[146:147], v[146:147], 0, v[150:151]
	v_lshlrev_b64 v[146:147], 2, v[146:147]
	v_lshl_add_u64 v[178:179], vcc, 0, v[146:147]
	v_lshl_add_u64 v[180:181], s[6:7], 0, v[146:147]
	global_load_dwordx4 v[148:151], v[178:179], off
	global_load_dwordx4 v[152:155], v[178:179], off offset:64
	global_load_dwordx4 v[156:159], v[178:179], off offset:128
	global_load_dwordx4 v[160:163], v[178:179], off offset:192
	s_mov_b64 s[56:57], 0x10000
	v_lshl_add_u64 v[146:147], v[178:179], 0, s[56:57]
	v_lshl_add_u64 v[190:191], v[180:181], 0, s[56:57]
	global_load_dwordx4 v[236:239], v[146:147], off
	global_load_dwordx4 v[240:243], v[146:147], off offset:64
	global_load_dwordx4 v[244:247], v[146:147], off offset:128
	global_load_dwordx4 v[248:251], v[146:147], off offset:192
	s_mov_b64 s[56:57], 0x20000
	v_lshl_add_u64 v[146:147], v[178:179], 0, s[56:57]
	v_lshl_add_u64 v[208:209], v[180:181], 0, s[56:57]
	global_load_dwordx4 v[194:197], v[146:147], off
	global_load_dwordx4 v[200:203], v[146:147], off offset:64
	global_load_dwordx4 v[204:207], v[146:147], off offset:128
	global_load_dwordx4 v[230:233], v[146:147], off offset:192
	s_waitcnt vmcnt(12)
	v_pk_mul_f32 v[130:131], v[130:131], s[40:41] op_sel_hi:[1,0]
	v_pk_mul_f32 v[132:133], v[132:133], s[40:41] op_sel_hi:[1,0]
	v_pk_mul_f32 v[134:135], v[134:135], s[40:41] op_sel_hi:[1,0]
	v_pk_mul_f32 v[136:137], v[136:137], s[40:41] op_sel_hi:[1,0]
	v_pk_mul_f32 v[138:139], v[138:139], s[40:41] op_sel_hi:[1,0]
	v_pk_mul_f32 v[140:141], v[140:141], s[40:41] op_sel_hi:[1,0]
	v_pk_mul_f32 v[142:143], v[142:143], s[40:41] op_sel_hi:[1,0]
	v_pk_mul_f32 v[144:145], v[144:145], s[40:41] op_sel_hi:[1,0]
	s_waitcnt vmcnt(8)
	v_pk_fma_f32 v[148:149], v[122:123], v[130:131], v[148:149]
	v_pk_fma_f32 v[150:151], v[124:125], v[132:133], v[150:151]
	v_pk_fma_f32 v[152:153], v[126:127], v[134:135], v[152:153]
	v_pk_fma_f32 v[154:155], v[128:129], v[136:137], v[154:155]
	v_pk_fma_f32 v[156:157], v[118:119], v[138:139], v[156:157]
	v_pk_fma_f32 v[158:159], v[120:121], v[140:141], v[158:159]
	v_pk_fma_f32 v[160:161], v[114:115], v[142:143], v[160:161]
	v_pk_fma_f32 v[162:163], v[116:117], v[144:145], v[162:163]
	global_store_dwordx4 v[180:181], v[148:151], off
	global_store_dwordx4 v[180:181], v[152:155], off offset:64
	global_store_dwordx4 v[180:181], v[156:159], off offset:128
	global_store_dwordx4 v[180:181], v[160:163], off offset:192
	s_mov_b64 s[56:57], 0x30000
	v_lshl_add_u64 v[146:147], v[178:179], 0, s[56:57]
	v_lshl_add_u64 v[164:165], v[180:181], 0, s[56:57]
	global_load_dwordx4 v[148:151], v[146:147], off
	global_load_dwordx4 v[152:155], v[146:147], off offset:64
	global_load_dwordx4 v[156:159], v[146:147], off offset:128
	global_load_dwordx4 v[160:163], v[146:147], off offset:192
	s_waitcnt vmcnt(12)
; #define GAS __attribute__((address_space(1)))
;     DI void operator()(const f32x4 (&acc)[2][2][4][2], const Unit& u, int wr, int wc, int fr, int fq) const {
;     ...
; #pragma unroll
;             for (int ai = 0; ai < 2; ++ai)
; #pragma unroll
;                 for (int m = 0; m < 4; ++m) { const size_t off = (size_t)(row0 + ai * HALF + m * 16) * DM + col0; f32x4 b[2][2];
; #pragma unroll
;                     for (int bj = 0; bj < 2; ++bj)
; #pragma unroll
;                         for (int n = 0; n < 2; ++n) b[bj][n] = *(const GAS f32x4*)(bp + off + bj * 32 + n * 16);
; #pragma unroll
;                     for (int bj = 0; bj < 2; ++bj)
; #pragma unroll
;                         for (int n = 0; n < 2; ++n) *(GAS f32x4*)(op + off + bj * 32 + n * 16) = b[bj][n] + gv[bj][n] * acc[ai][bj][m][n]; }
	v_pk_fma_f32 v[236:237], v[110:111], v[130:131], v[236:237]
	v_pk_fma_f32 v[238:239], v[112:113], v[132:133], v[238:239]
	v_pk_fma_f32 v[240:241], v[106:107], v[134:135], v[240:241]
	v_pk_fma_f32 v[242:243], v[108:109], v[136:137], v[242:243]
	v_pk_fma_f32 v[244:245], v[102:103], v[138:139], v[244:245]
	v_pk_fma_f32 v[246:247], v[104:105], v[140:141], v[246:247]
	v_pk_fma_f32 v[248:249], v[98:99], v[142:143], v[248:249]
	v_pk_fma_f32 v[250:251], v[100:101], v[144:145], v[250:251]
	global_store_dwordx4 v[190:191], v[236:239], off
	global_store_dwordx4 v[190:191], v[240:243], off offset:64
	global_store_dwordx4 v[190:191], v[244:247], off offset:128
	global_store_dwordx4 v[190:191], v[248:251], off offset:192
	s_mov_b64 s[56:57], 0x80000
	v_lshl_add_u64 v[146:147], v[178:179], 0, s[56:57]
	v_lshl_add_u64 v[190:191], v[180:181], 0, s[56:57]
	global_load_dwordx4 v[236:239], v[146:147], off
	global_load_dwordx4 v[240:243], v[146:147], off offset:64
	global_load_dwordx4 v[244:247], v[146:147], off offset:128
	global_load_dwordx4 v[248:251], v[146:147], off offset:192
	s_waitcnt vmcnt(16)
	v_pk_fma_f32 v[194:195], v[94:95], v[130:131], v[194:195]
	v_pk_fma_f32 v[196:197], v[96:97], v[132:133], v[196:197]
	v_pk_fma_f32 v[200:201], v[90:91], v[134:135], v[200:201]
	v_pk_fma_f32 v[202:203], v[92:93], v[136:137], v[202:203]
	v_pk_fma_f32 v[204:205], v[86:87], v[138:139], v[204:205]
	v_pk_fma_f32 v[206:207], v[88:89], v[140:141], v[206:207]
	v_pk_fma_f32 v[230:231], v[82:83], v[142:143], v[230:231]
	v_pk_fma_f32 v[232:233], v[84:85], v[144:145], v[232:233]
	global_store_dwordx4 v[208:209], v[194:197], off
	global_store_dwordx4 v[208:209], v[200:203], off offset:64
	global_store_dwordx4 v[208:209], v[204:207], off offset:128
	global_store_dwordx4 v[208:209], v[230:233], off offset:192
	s_mov_b64 s[56:57], 0x90000
	v_lshl_add_u64 v[146:147], v[178:179], 0, s[56:57]
	v_lshl_add_u64 v[208:209], v[180:181], 0, s[56:57]
	global_load_dwordx4 v[194:197], v[146:147], off
	global_load_dwordx4 v[200:203], v[146:147], off offset:64
	global_load_dwordx4 v[204:207], v[146:147], off offset:128
	global_load_dwordx4 v[230:233], v[146:147], off offset:192
	s_waitcnt vmcnt(16)
	v_pk_fma_f32 v[148:149], v[78:79], v[130:131], v[148:149]
	v_pk_fma_f32 v[150:151], v[80:81], v[132:133], v[150:151]
	v_pk_fma_f32 v[152:153], v[74:75], v[134:135], v[152:153]
	v_pk_fma_f32 v[154:155], v[76:77], v[136:137], v[154:155]
	v_pk_fma_f32 v[156:157], v[70:71], v[138:139], v[156:157]
	v_pk_fma_f32 v[158:159], v[72:73], v[140:141], v[158:159]
	v_pk_fma_f32 v[160:161], v[66:67], v[142:143], v[160:161]
	v_pk_fma_f32 v[162:163], v[68:69], v[144:145], v[162:163]
	global_store_dwordx4 v[164:165], v[148:151], off
	global_store_dwordx4 v[164:165], v[152:155], off offset:64
	global_store_dwordx4 v[164:165], v[156:159], off offset:128
	global_store_dwordx4 v[164:165], v[160:163], off offset:192
	s_mov_b64 s[56:57], 0xa0000
	v_lshl_add_u64 v[146:147], v[178:179], 0, s[56:57]
	v_lshl_add_u64 v[164:165], v[180:181], 0, s[56:57]
	global_load_dwordx4 v[148:151], v[146:147], off
	global_load_dwordx4 v[152:155], v[146:147], off offset:64
	global_load_dwordx4 v[156:159], v[146:147], off offset:128
	global_load_dwordx4 v[160:163], v[146:147], off offset:192
	s_waitcnt vmcnt(16)
	v_pk_fma_f32 v[236:237], v[62:63], v[130:131], v[236:237]
	v_pk_fma_f32 v[238:239], v[64:65], v[132:133], v[238:239]
	v_pk_fma_f32 v[240:241], v[58:59], v[134:135], v[240:241]
	v_pk_fma_f32 v[242:243], v[60:61], v[136:137], v[242:243]
	v_pk_fma_f32 v[244:245], v[54:55], v[138:139], v[244:245]
	v_pk_fma_f32 v[246:247], v[56:57], v[140:141], v[246:247]
	v_pk_fma_f32 v[248:249], v[50:51], v[142:143], v[248:249]
	v_pk_fma_f32 v[250:251], v[52:53], v[144:145], v[250:251]
	global_store_dwordx4 v[190:191], v[236:239], off
	global_store_dwordx4 v[190:191], v[240:243], off offset:64
	global_store_dwordx4 v[190:191], v[244:247], off offset:128
	global_store_dwordx4 v[190:191], v[248:251], off offset:192
	s_mov_b64 s[56:57], 0xb0000
	v_lshl_add_u64 v[146:147], v[178:179], 0, s[56:57]
	v_lshl_add_u64 v[190:191], v[180:181], 0, s[56:57]
	global_load_dwordx4 v[236:239], v[146:147], off
	global_load_dwordx4 v[240:243], v[146:147], off offset:64
	global_load_dwordx4 v[244:247], v[146:147], off offset:128
	global_load_dwordx4 v[248:251], v[146:147], off offset:192
	s_waitcnt vmcnt(16)
	v_pk_fma_f32 v[194:195], v[46:47], v[130:131], v[194:195]
	v_pk_fma_f32 v[196:197], v[48:49], v[132:133], v[196:197]
	v_pk_fma_f32 v[200:201], v[42:43], v[134:135], v[200:201]
	v_pk_fma_f32 v[202:203], v[44:45], v[136:137], v[202:203]
	v_pk_fma_f32 v[204:205], v[38:39], v[138:139], v[204:205]
	v_pk_fma_f32 v[206:207], v[40:41], v[140:141], v[206:207]
	v_pk_fma_f32 v[230:231], v[34:35], v[142:143], v[230:231]
	v_pk_fma_f32 v[232:233], v[36:37], v[144:145], v[232:233]
	global_store_dwordx4 v[208:209], v[194:197], off
	global_store_dwordx4 v[208:209], v[200:203], off offset:64
	global_store_dwordx4 v[208:209], v[204:207], off offset:128
	global_store_dwordx4 v[208:209], v[230:233], off offset:192
	s_waitcnt vmcnt(12)
	v_pk_fma_f32 v[148:149], v[30:31], v[130:131], v[148:149]
	v_pk_fma_f32 v[150:151], v[32:33], v[132:133], v[150:151]
	v_pk_fma_f32 v[152:153], v[26:27], v[134:135], v[152:153]
	v_pk_fma_f32 v[154:155], v[28:29], v[136:137], v[154:155]
	v_pk_fma_f32 v[156:157], v[22:23], v[138:139], v[156:157]
	v_pk_fma_f32 v[158:159], v[24:25], v[140:141], v[158:159]
	v_pk_fma_f32 v[160:161], v[18:19], v[142:143], v[160:161]
	v_pk_fma_f32 v[162:163], v[20:21], v[144:145], v[162:163]
	global_store_dwordx4 v[164:165], v[148:151], off
	global_store_dwordx4 v[164:165], v[152:155], off offset:64
	global_store_dwordx4 v[164:165], v[156:159], off offset:128
	global_store_dwordx4 v[164:165], v[160:163], off offset:192
	s_waitcnt vmcnt(8)
	v_pk_fma_f32 v[236:237], v[14:15], v[130:131], v[236:237]
	v_pk_fma_f32 v[238:239], v[16:17], v[132:133], v[238:239]
	v_pk_fma_f32 v[240:241], v[10:11], v[134:135], v[240:241]
	v_pk_fma_f32 v[242:243], v[12:13], v[136:137], v[242:243]
	v_pk_fma_f32 v[244:245], v[6:7], v[138:139], v[244:245]
	v_pk_fma_f32 v[246:247], v[8:9], v[140:141], v[246:247]
	v_pk_fma_f32 v[248:249], v[2:3], v[142:143], v[248:249]
	v_pk_fma_f32 v[250:251], v[4:5], v[144:145], v[250:251]
	global_store_dwordx4 v[190:191], v[236:239], off
	global_store_dwordx4 v[190:191], v[240:243], off offset:64
	global_store_dwordx4 v[190:191], v[244:247], off offset:128
	global_store_dwordx4 v[190:191], v[248:251], off offset:192
	s_mov_b64 s[56:57], 0xb0000
	s_mov_b64 s[6:7], 0
